# cross-XCD release wait moved after the first gate loads of the mix-GEMM epilogue (poll overlaps those loads), on top of the overlapped-first-poll variant
# speedup vs baseline: 1.0063x; 1.0063x over previous
.LBB0_1474:
	v_lshl_add_u32 v146, s42, 8, v150
	v_lshl_or_b32 v144, s63, 8, v158
	v_ashrrev_i32_e32 v147, 31, v146
	v_lshlrev_b64 v[162:163], 12, v[146:147]
	v_ashrrev_i32_e32 v145, 31, v144
	v_lshl_add_u64 v[162:163], s[36:37], 0, v[162:163]
	v_lshlrev_b64 v[144:145], 1, v[144:145]
	v_lshl_add_u64 v[166:167], v[162:163], 0, v[144:145]
	global_load_dwordx4 v[162:165], v[166:167], off
	s_nop 0
	global_load_dwordx4 v[166:169], v[166:167], off offset:256
	s_cmp_eq_u32 s98, 3
	s_cbranch_scc0 .Lwb_skip
	s_mov_b32 s98, 4
	v_cmp_gt_u32_e32 vcc, 64, v199
	s_cbranch_vccz .Lwb_bar
	v_mov_b32_e32 v176, 0xfc03500
	s_mov_b32 s100, 0x8000

.Lwb_skip:
	v_or_b32_e32 v170, 16, v146
	v_lshlrev_b64 v[172:173], 11, v[146:147]
	v_ashrrev_i32_e32 v171, 31, v170
	v_lshl_add_u64 v[172:173], s[14:15], 0, v[172:173]
	v_lshlrev_b64 v[174:175], 12, v[170:171]
	v_lshl_add_u64 v[172:173], v[172:173], 0, v[144:145]
	v_lshl_add_u64 v[174:175], s[36:37], 0, v[174:175]
	v_lshl_add_u64 v[174:175], v[174:175], 0, v[144:145]
	s_andn2_b64 vcc, exec, s[2:3]
	s_mov_b64 s[2:3], -1
	s_waitcnt vmcnt(0)
	v_lshlrev_b32_e32 v176, 16, v162
	v_and_b32_e32 v177, 0xffff0000, v162
	v_lshlrev_b32_e32 v162, 16, v163
	v_and_b32_e32 v163, 0xffff0000, v163
	v_lshlrev_b32_e32 v178, 16, v164
	v_and_b32_e32 v179, 0xffff0000, v164
	v_lshlrev_b32_e32 v164, 16, v165
	v_and_b32_e32 v165, 0xffff0000, v165
	v_lshlrev_b32_e32 v180, 16, v166
	v_and_b32_e32 v181, 0xffff0000, v166
	v_lshlrev_b32_e32 v166, 16, v167
	v_and_b32_e32 v167, 0xffff0000, v167
	v_lshlrev_b32_e32 v182, 16, v168
	v_and_b32_e32 v183, 0xffff0000, v168
	v_lshlrev_b32_e32 v168, 16, v169
	v_and_b32_e32 v169, 0xffff0000, v169
	v_pk_mul_f32 v[126:127], v[126:127], v[162:163]
	v_pk_mul_f32 v[124:125], v[124:125], v[176:177]
	v_pk_mul_f32 v[122:123], v[122:123], v[164:165]
	v_pk_mul_f32 v[120:121], v[120:121], v[178:179]
	v_pk_mul_f32 v[162:163], v[118:119], v[166:167]
	v_pk_mul_f32 v[164:165], v[116:117], v[180:181]
	v_cvt_pk_bf16_f32 v116, v124, v125
	v_cvt_pk_bf16_f32 v117, v126, v127
	v_cvt_pk_bf16_f32 v118, v120, v121
	v_cvt_pk_bf16_f32 v119, v122, v123
	v_pk_mul_f32 v[120:121], v[114:115], v[168:169]
	v_pk_mul_f32 v[114:115], v[112:113], v[182:183]
	global_store_dwordx4 v[172:173], v[116:119], off
	v_cvt_pk_bf16_f32 v112, v164, v165
	v_cvt_pk_bf16_f32 v113, v162, v163
	v_cvt_pk_bf16_f32 v114, v114, v115
	v_cvt_pk_bf16_f32 v115, v120, v121
	global_load_dwordx4 v[116:119], v[174:175], off
	v_or_b32_e32 v120, 32, v146
	global_store_dwordx4 v[172:173], v[112:115], off offset:256
	global_load_dwordx4 v[112:115], v[174:175], off offset:256
	v_ashrrev_i32_e32 v121, 31, v120
	v_lshlrev_b64 v[122:123], 11, v[170:171]
	v_lshlrev_b64 v[124:125], 12, v[120:121]
	v_lshl_add_u64 v[122:123], s[14:15], 0, v[122:123]
	v_lshl_add_u64 v[124:125], s[36:37], 0, v[124:125]
	v_lshl_add_u64 v[122:123], v[122:123], 0, v[144:145]
	v_lshl_add_u64 v[124:125], v[124:125], 0, v[144:145]
	s_waitcnt vmcnt(2)
	v_lshlrev_b32_e32 v126, 16, v116
	v_and_b32_e32 v127, 0xffff0000, v116
	v_lshlrev_b32_e32 v116, 16, v117
	v_and_b32_e32 v117, 0xffff0000, v117
	v_lshlrev_b32_e32 v162, 16, v118
	v_and_b32_e32 v163, 0xffff0000, v118
	v_lshlrev_b32_e32 v118, 16, v119
	v_and_b32_e32 v119, 0xffff0000, v119
	s_waitcnt vmcnt(0)
	v_lshlrev_b32_e32 v164, 16, v112
	v_and_b32_e32 v165, 0xffff0000, v112
	v_lshlrev_b32_e32 v112, 16, v113
	v_and_b32_e32 v113, 0xffff0000, v113
	v_lshlrev_b32_e32 v166, 16, v114
	v_and_b32_e32 v167, 0xffff0000, v114
	v_lshlrev_b32_e32 v114, 16, v115
	v_and_b32_e32 v115, 0xffff0000, v115
	v_pk_mul_f32 v[110:111], v[110:111], v[116:117]
	v_pk_mul_f32 v[108:109], v[108:109], v[126:127]
	v_pk_mul_f32 v[106:107], v[106:107], v[118:119]
	v_pk_mul_f32 v[104:105], v[104:105], v[162:163]
	v_pk_mul_f32 v[112:113], v[102:103], v[112:113]
	v_pk_mul_f32 v[116:117], v[100:101], v[164:165]
	v_cvt_pk_bf16_f32 v100, v108, v109
	v_cvt_pk_bf16_f32 v101, v110, v111
	v_cvt_pk_bf16_f32 v102, v104, v105
	v_cvt_pk_bf16_f32 v103, v106, v107
	v_pk_mul_f32 v[104:105], v[98:99], v[114:115]
	v_pk_mul_f32 v[98:99], v[96:97], v[166:167]
	global_store_dwordx4 v[122:123], v[100:103], off
	v_cvt_pk_bf16_f32 v96, v116, v117
	v_cvt_pk_bf16_f32 v97, v112, v113
	v_cvt_pk_bf16_f32 v98, v98, v99
	v_cvt_pk_bf16_f32 v99, v104, v105
	global_load_dwordx4 v[100:103], v[124:125], off
	v_or_b32_e32 v104, 48, v146
	global_store_dwordx4 v[122:123], v[96:99], off offset:256
	global_load_dwordx4 v[96:99], v[124:125], off offset:256
	v_ashrrev_i32_e32 v105, 31, v104
	v_lshlrev_b64 v[106:107], 11, v[120:121]
	v_lshlrev_b64 v[108:109], 12, v[104:105]
	v_lshl_add_u64 v[106:107], s[14:15], 0, v[106:107]
	v_lshl_add_u64 v[108:109], s[36:37], 0, v[108:109]
	v_lshl_add_u64 v[106:107], v[106:107], 0, v[144:145]
	v_lshl_add_u64 v[108:109], v[108:109], 0, v[144:145]
	s_waitcnt vmcnt(2)
	v_lshlrev_b32_e32 v110, 16, v100
	v_and_b32_e32 v111, 0xffff0000, v100
	v_lshlrev_b32_e32 v100, 16, v101
	v_and_b32_e32 v101, 0xffff0000, v101
	v_lshlrev_b32_e32 v112, 16, v102
	v_and_b32_e32 v113, 0xffff0000, v102
	v_lshlrev_b32_e32 v102, 16, v103
	v_and_b32_e32 v103, 0xffff0000, v103
	s_waitcnt vmcnt(0)
	v_lshlrev_b32_e32 v114, 16, v96
	v_and_b32_e32 v115, 0xffff0000, v96
	v_lshlrev_b32_e32 v96, 16, v97
	v_and_b32_e32 v97, 0xffff0000, v97
	v_lshlrev_b32_e32 v116, 16, v98
	v_and_b32_e32 v117, 0xffff0000, v98
	v_lshlrev_b32_e32 v98, 16, v99
	v_and_b32_e32 v99, 0xffff0000, v99
	v_pk_mul_f32 v[94:95], v[94:95], v[100:101]
	v_pk_mul_f32 v[92:93], v[92:93], v[110:111]
	v_pk_mul_f32 v[90:91], v[90:91], v[102:103]
	v_pk_mul_f32 v[88:89], v[88:89], v[112:113]
	v_pk_mul_f32 v[96:97], v[86:87], v[96:97]
	v_pk_mul_f32 v[100:101], v[84:85], v[114:115]
	v_cvt_pk_bf16_f32 v84, v92, v93
	v_cvt_pk_bf16_f32 v85, v94, v95
	v_cvt_pk_bf16_f32 v86, v88, v89
	v_cvt_pk_bf16_f32 v87, v90, v91
	v_pk_mul_f32 v[88:89], v[82:83], v[98:99]
	v_pk_mul_f32 v[82:83], v[80:81], v[116:117]
	global_store_dwordx4 v[106:107], v[84:87], off
	v_cvt_pk_bf16_f32 v80, v100, v101
	v_cvt_pk_bf16_f32 v81, v96, v97
	v_cvt_pk_bf16_f32 v82, v82, v83
	v_cvt_pk_bf16_f32 v83, v88, v89
	global_load_dwordx4 v[84:87], v[108:109], off
	v_add_u32_e32 v88, 0x80, v146
	global_store_dwordx4 v[106:107], v[80:83], off offset:256
	global_load_dwordx4 v[80:83], v[108:109], off offset:256
	v_ashrrev_i32_e32 v89, 31, v88
	v_lshlrev_b64 v[90:91], 11, v[104:105]
	v_lshlrev_b64 v[92:93], 12, v[88:89]
	v_lshl_add_u64 v[90:91], s[14:15], 0, v[90:91]
	v_lshl_add_u64 v[92:93], s[36:37], 0, v[92:93]
	v_lshl_add_u64 v[90:91], v[90:91], 0, v[144:145]
	v_lshl_add_u64 v[92:93], v[92:93], 0, v[144:145]
	s_waitcnt vmcnt(2)
	v_lshlrev_b32_e32 v94, 16, v84
	v_and_b32_e32 v95, 0xffff0000, v84
	v_lshlrev_b32_e32 v84, 16, v85
	v_and_b32_e32 v85, 0xffff0000, v85
	v_lshlrev_b32_e32 v96, 16, v86
	v_and_b32_e32 v97, 0xffff0000, v86
	v_lshlrev_b32_e32 v86, 16, v87
	v_and_b32_e32 v87, 0xffff0000, v87
	s_waitcnt vmcnt(0)
	v_lshlrev_b32_e32 v98, 16, v80
	v_and_b32_e32 v99, 0xffff0000, v80
	v_lshlrev_b32_e32 v80, 16, v81
	v_and_b32_e32 v81, 0xffff0000, v81
	v_lshlrev_b32_e32 v100, 16, v82
	v_and_b32_e32 v101, 0xffff0000, v82
	v_lshlrev_b32_e32 v82, 16, v83
	v_and_b32_e32 v83, 0xffff0000, v83
	v_pk_mul_f32 v[78:79], v[78:79], v[84:85]
	v_pk_mul_f32 v[76:77], v[76:77], v[94:95]
	v_pk_mul_f32 v[74:75], v[74:75], v[86:87]
	v_pk_mul_f32 v[72:73], v[72:73], v[96:97]
	v_pk_mul_f32 v[80:81], v[70:71], v[80:81]
	v_pk_mul_f32 v[84:85], v[68:69], v[98:99]
	v_cvt_pk_bf16_f32 v68, v76, v77
	v_cvt_pk_bf16_f32 v69, v78, v79
	v_cvt_pk_bf16_f32 v70, v72, v73
	v_cvt_pk_bf16_f32 v71, v74, v75
	v_pk_mul_f32 v[72:73], v[66:67], v[82:83]
	v_pk_mul_f32 v[66:67], v[64:65], v[100:101]
	global_store_dwordx4 v[90:91], v[68:71], off
	v_cvt_pk_bf16_f32 v64, v84, v85
	v_cvt_pk_bf16_f32 v65, v80, v81
	v_cvt_pk_bf16_f32 v66, v66, v67
	v_cvt_pk_bf16_f32 v67, v72, v73
	global_load_dwordx4 v[68:71], v[92:93], off
	v_add_u32_e32 v72, 0x90, v146
	global_store_dwordx4 v[90:91], v[64:67], off offset:256
	global_load_dwordx4 v[64:67], v[92:93], off offset:256
	v_ashrrev_i32_e32 v73, 31, v72
	v_lshlrev_b64 v[74:75], 11, v[88:89]
	v_lshlrev_b64 v[76:77], 12, v[72:73]
	v_lshl_add_u64 v[74:75], s[14:15], 0, v[74:75]
	v_lshl_add_u64 v[76:77], s[36:37], 0, v[76:77]
	v_lshl_add_u64 v[74:75], v[74:75], 0, v[144:145]
	v_lshl_add_u64 v[76:77], v[76:77], 0, v[144:145]
	s_waitcnt vmcnt(2)
	v_lshlrev_b32_e32 v78, 16, v68
	v_and_b32_e32 v79, 0xffff0000, v68
	v_lshlrev_b32_e32 v68, 16, v69
	v_and_b32_e32 v69, 0xffff0000, v69
	v_lshlrev_b32_e32 v80, 16, v70
	v_and_b32_e32 v81, 0xffff0000, v70
	v_lshlrev_b32_e32 v70, 16, v71
	v_and_b32_e32 v71, 0xffff0000, v71
	s_waitcnt vmcnt(0)
	v_lshlrev_b32_e32 v82, 16, v64
	v_and_b32_e32 v83, 0xffff0000, v64
	v_lshlrev_b32_e32 v64, 16, v65
	v_and_b32_e32 v65, 0xffff0000, v65
	v_lshlrev_b32_e32 v84, 16, v66
	v_and_b32_e32 v85, 0xffff0000, v66
	v_lshlrev_b32_e32 v66, 16, v67
	v_and_b32_e32 v67, 0xffff0000, v67
	v_pk_mul_f32 v[62:63], v[62:63], v[68:69]
	v_pk_mul_f32 v[60:61], v[60:61], v[78:79]
	v_pk_mul_f32 v[58:59], v[58:59], v[70:71]
	v_pk_mul_f32 v[56:57], v[56:57], v[80:81]
	v_pk_mul_f32 v[64:65], v[54:55], v[64:65]
	v_pk_mul_f32 v[68:69], v[52:53], v[82:83]
	v_cvt_pk_bf16_f32 v52, v60, v61
	v_cvt_pk_bf16_f32 v53, v62, v63
	v_cvt_pk_bf16_f32 v54, v56, v57
	v_cvt_pk_bf16_f32 v55, v58, v59
	v_pk_mul_f32 v[56:57], v[50:51], v[66:67]
	v_pk_mul_f32 v[50:51], v[48:49], v[84:85]
	global_store_dwordx4 v[74:75], v[52:55], off
	v_cvt_pk_bf16_f32 v48, v68, v69
	v_cvt_pk_bf16_f32 v49, v64, v65
	v_cvt_pk_bf16_f32 v50, v50, v51
	v_cvt_pk_bf16_f32 v51, v56, v57
	global_load_dwordx4 v[52:55], v[76:77], off
	v_add_u32_e32 v56, 0xa0, v146
	global_store_dwordx4 v[74:75], v[48:51], off offset:256
	global_load_dwordx4 v[48:51], v[76:77], off offset:256
	v_ashrrev_i32_e32 v57, 31, v56
	v_lshlrev_b64 v[58:59], 11, v[72:73]
	v_lshlrev_b64 v[60:61], 12, v[56:57]
	v_lshl_add_u64 v[58:59], s[14:15], 0, v[58:59]
	v_lshl_add_u64 v[60:61], s[36:37], 0, v[60:61]
	v_lshl_add_u64 v[58:59], v[58:59], 0, v[144:145]
	v_lshl_add_u64 v[60:61], v[60:61], 0, v[144:145]
	s_waitcnt vmcnt(2)
	v_lshlrev_b32_e32 v62, 16, v52
	v_and_b32_e32 v63, 0xffff0000, v52
	v_lshlrev_b32_e32 v52, 16, v53
	v_and_b32_e32 v53, 0xffff0000, v53
	v_lshlrev_b32_e32 v64, 16, v54
	v_and_b32_e32 v65, 0xffff0000, v54
	v_lshlrev_b32_e32 v54, 16, v55
	v_and_b32_e32 v55, 0xffff0000, v55
	s_waitcnt vmcnt(0)
	v_lshlrev_b32_e32 v66, 16, v48
	v_and_b32_e32 v67, 0xffff0000, v48
	v_lshlrev_b32_e32 v48, 16, v49
	v_and_b32_e32 v49, 0xffff0000, v49
	v_lshlrev_b32_e32 v68, 16, v50
	v_and_b32_e32 v69, 0xffff0000, v50
	v_lshlrev_b32_e32 v50, 16, v51
	v_and_b32_e32 v51, 0xffff0000, v51
	v_pk_mul_f32 v[46:47], v[46:47], v[52:53]
	v_pk_mul_f32 v[44:45], v[44:45], v[62:63]
	v_pk_mul_f32 v[42:43], v[42:43], v[54:55]
	v_pk_mul_f32 v[40:41], v[40:41], v[64:65]
	v_pk_mul_f32 v[48:49], v[38:39], v[48:49]
	v_pk_mul_f32 v[52:53], v[36:37], v[66:67]
	v_cvt_pk_bf16_f32 v36, v44, v45
	v_cvt_pk_bf16_f32 v37, v46, v47
	v_cvt_pk_bf16_f32 v38, v40, v41
	v_cvt_pk_bf16_f32 v39, v42, v43
	v_pk_mul_f32 v[40:41], v[34:35], v[50:51]
	v_pk_mul_f32 v[34:35], v[32:33], v[68:69]
	global_store_dwordx4 v[58:59], v[36:39], off
	v_cvt_pk_bf16_f32 v32, v52, v53
	v_cvt_pk_bf16_f32 v33, v48, v49
	v_cvt_pk_bf16_f32 v34, v34, v35
	v_cvt_pk_bf16_f32 v35, v40, v41
	global_load_dwordx4 v[36:39], v[60:61], off
	v_add_u32_e32 v40, 0xb0, v146
	global_store_dwordx4 v[58:59], v[32:35], off offset:256
	global_load_dwordx4 v[32:35], v[60:61], off offset:256
	v_ashrrev_i32_e32 v41, 31, v40
	v_lshlrev_b64 v[42:43], 11, v[56:57]
	v_lshlrev_b64 v[44:45], 12, v[40:41]
	v_lshl_add_u64 v[42:43], s[14:15], 0, v[42:43]
	v_lshl_add_u64 v[44:45], s[36:37], 0, v[44:45]
	v_lshl_add_u64 v[42:43], v[42:43], 0, v[144:145]
	v_lshl_add_u64 v[44:45], v[44:45], 0, v[144:145]
	s_waitcnt vmcnt(2)
	v_lshlrev_b32_e32 v46, 16, v36
	v_and_b32_e32 v47, 0xffff0000, v36
	v_lshlrev_b32_e32 v36, 16, v37
	v_and_b32_e32 v37, 0xffff0000, v37
	v_lshlrev_b32_e32 v48, 16, v38
	v_and_b32_e32 v49, 0xffff0000, v38
	v_lshlrev_b32_e32 v38, 16, v39
	v_and_b32_e32 v39, 0xffff0000, v39
	s_waitcnt vmcnt(0)
	v_lshlrev_b32_e32 v50, 16, v32
	v_and_b32_e32 v51, 0xffff0000, v32
	v_lshlrev_b32_e32 v32, 16, v33
	v_and_b32_e32 v33, 0xffff0000, v33
	v_lshlrev_b32_e32 v52, 16, v34
	v_and_b32_e32 v53, 0xffff0000, v34
	v_lshlrev_b32_e32 v34, 16, v35
	v_and_b32_e32 v35, 0xffff0000, v35
	v_pk_mul_f32 v[30:31], v[30:31], v[36:37]
	v_pk_mul_f32 v[28:29], v[28:29], v[46:47]
	v_pk_mul_f32 v[26:27], v[26:27], v[38:39]
	v_pk_mul_f32 v[24:25], v[24:25], v[48:49]
	v_pk_mul_f32 v[32:33], v[22:23], v[32:33]
	v_pk_mul_f32 v[36:37], v[20:21], v[50:51]
	v_cvt_pk_bf16_f32 v20, v28, v29
	v_cvt_pk_bf16_f32 v21, v30, v31
	v_cvt_pk_bf16_f32 v22, v24, v25
	v_cvt_pk_bf16_f32 v23, v26, v27
	v_pk_mul_f32 v[24:25], v[18:19], v[34:35]
	v_pk_mul_f32 v[18:19], v[16:17], v[52:53]
	global_store_dwordx4 v[42:43], v[20:23], off
	v_cvt_pk_bf16_f32 v16, v36, v37
	v_cvt_pk_bf16_f32 v17, v32, v33
	v_cvt_pk_bf16_f32 v18, v18, v19
	v_cvt_pk_bf16_f32 v19, v24, v25
	global_load_dwordx4 v[20:23], v[44:45], off
	v_lshlrev_b64 v[24:25], 11, v[40:41]
	global_store_dwordx4 v[42:43], v[16:19], off offset:256
	global_load_dwordx4 v[16:19], v[44:45], off offset:256
	v_lshl_add_u64 v[24:25], s[14:15], 0, v[24:25]
	v_lshl_add_u64 v[24:25], v[24:25], 0, v[144:145]
	s_waitcnt vmcnt(2)
	v_lshlrev_b32_e32 v26, 16, v20
	v_and_b32_e32 v27, 0xffff0000, v20
	v_lshlrev_b32_e32 v20, 16, v21
	v_and_b32_e32 v21, 0xffff0000, v21
	v_lshlrev_b32_e32 v28, 16, v22
	v_and_b32_e32 v29, 0xffff0000, v22
	v_lshlrev_b32_e32 v22, 16, v23
	v_and_b32_e32 v23, 0xffff0000, v23
	s_waitcnt vmcnt(0)
	v_lshlrev_b32_e32 v30, 16, v16
	v_and_b32_e32 v31, 0xffff0000, v16
	v_lshlrev_b32_e32 v16, 16, v17
	v_and_b32_e32 v17, 0xffff0000, v17
	v_lshlrev_b32_e32 v32, 16, v18
	v_and_b32_e32 v33, 0xffff0000, v18
	v_lshlrev_b32_e32 v18, 16, v19
	v_and_b32_e32 v19, 0xffff0000, v19
	v_pk_mul_f32 v[14:15], v[14:15], v[20:21]
	v_pk_mul_f32 v[12:13], v[12:13], v[26:27]
	v_pk_mul_f32 v[10:11], v[10:11], v[22:23]
	v_pk_mul_f32 v[8:9], v[8:9], v[28:29]
	v_pk_mul_f32 v[6:7], v[6:7], v[16:17]
	v_pk_mul_f32 v[4:5], v[4:5], v[30:31]
	v_pk_mul_f32 v[16:17], v[2:3], v[18:19]
	v_pk_mul_f32 v[18:19], v[0:1], v[32:33]
	v_cvt_pk_bf16_f32 v0, v12, v13
	v_cvt_pk_bf16_f32 v1, v14, v15
	v_cvt_pk_bf16_f32 v2, v8, v9
	v_cvt_pk_bf16_f32 v3, v10, v11
	v_cvt_pk_bf16_f32 v4, v4, v5
	v_cvt_pk_bf16_f32 v5, v6, v7
	v_cvt_pk_bf16_f32 v6, v18, v19
	v_cvt_pk_bf16_f32 v7, v16, v17
	global_store_dwordx4 v[24:25], v[0:3], off
	global_store_dwordx4 v[24:25], v[4:7], off offset:256
	s_cbranch_vccnz .LBB0_1463
	s_andn2_b64 vcc, exec, s[6:7]
	s_cbranch_vccnz .LBB0_1462
	s_barrier
	s_branch .LBB0_1462
